# v38 plus hand-written peer_n (LN2): ln2 gain/bias loaded once per wave, one row normalised while the next row's x1/y/gate loads are in flight, no per-store vmcnt(0)
# speedup vs baseline: 1.0076x; 1.0030x over previous
; __device__ void phase_peer_n(const Params& p, int bid, int nb) {
;     ...
;   for (int tb = bid * 4 + w; tb < NTOK; tb += NR * stride) {
;     float zz[NR][16], mu[NR], rstd[NR];
;     int tt[NR];
; #pragma unroll
;     for (int u = 0; u < NR; ++u) {
;       tt[u] = (tb + u * stride < NTOK) ? tb + u * stride : tb;
;       const int t = tt[u], b = t >> 13;
;       const float* gate = ada + b * 6144 + 5120;
;       const float* orow = p.out + (size_t)t * 1024;
;       const float* xrow = (const float*)(p.ws + OFF_X1) + (size_t)t * 1024;
; #pragma unroll
;       for (int q = 0; q < 4; ++q) {
;         const int d0 = 256 * q + 4 * lane;
;         float4 xa = *(const float4*)(xrow + d0), ga = *(const float4*)(gate + d0), ya = *(const float4*)(orow + d0);
;         zz[u][4 * q + 0] = ALPHA * xa.x + ga.x * ya.x; zz[u][4 * q + 1] = ALPHA * xa.y + ga.y * ya.y;
;         zz[u][4 * q + 2] = ALPHA * xa.z + ga.z * ya.z; zz[u][4 * q + 3] = ALPHA * xa.w + ga.w * ya.w;
;       }
;     }
.LBB0_778:
	s_or_b64 exec, exec, s[0:1]
	s_waitcnt lgkmcnt(0)
	s_barrier
	s_waitcnt vmcnt(6)
	v_and_b32_e32 v1, 63, v118
	v_lshrrev_b32_e32 v4, 6, v118
	v_lshlrev_b32_e32 v2, 4, v1
	v_add_u32_e32 v4, s24, v4
	v_readlane_b32 s4, v182, 17
	v_readlane_b32 s5, v182, 18
	v_readfirstlane_b32 s0, v4
	v_mov_b32_e32 v3, 0x3727c5ac
	s_lshl_b32 s1, s94, 2
	s_add_u32 s6, s92, 0xab20000
	s_addc_u32 s7, s93, 0
	s_add_u32 s8, s92, 0x5000
	s_addc_u32 s9, s93, 0
	s_nop 3
	global_load_dwordx4 v[200:203], v2, s[4:5]
	global_load_dwordx4 v[204:207], v2, s[4:5] offset:1024
	global_load_dwordx4 v[208:211], v2, s[4:5] offset:2048
	global_load_dwordx4 v[212:215], v2, s[4:5] offset:3072
	global_load_dwordx4 v[216:219], v2, s[88:89]
	global_load_dwordx4 v[220:223], v2, s[88:89] offset:1024
	global_load_dwordx4 v[224:227], v2, s[88:89] offset:2048
	global_load_dwordx4 v[228:231], v2, s[88:89] offset:3072
	s_lshl_b32 s17, s0, 12
	s_add_u32 s10, s6, s17
	s_addc_u32 s11, s7, 0
	global_load_dwordx4 v[8:11], v2, s[10:11]
	global_load_dwordx4 v[12:15], v2, s[10:11] offset:1024
	global_load_dwordx4 v[16:19], v2, s[10:11] offset:2048
	global_load_dwordx4 v[20:23], v2, s[10:11] offset:3072
	s_add_u32 s12, s90, s17
	s_addc_u32 s13, s91, 0
	global_load_dwordx4 v[24:27], v2, s[12:13]
	global_load_dwordx4 v[28:31], v2, s[12:13] offset:1024
	global_load_dwordx4 v[32:35], v2, s[12:13] offset:2048
	global_load_dwordx4 v[36:39], v2, s[12:13] offset:3072
	s_lshr_b32 s18, s0, 13
	s_mul_i32 s18, s18, 0x6000
	s_add_u32 s10, s8, s18
	s_addc_u32 s11, s9, 0
	global_load_dwordx4 v[40:43], v2, s[10:11]
	global_load_dwordx4 v[44:47], v2, s[10:11] offset:1024
	global_load_dwordx4 v[48:51], v2, s[10:11] offset:2048
	global_load_dwordx4 v[52:55], v2, s[10:11] offset:3072
	s_mov_b32 s16, 1
.Lpn_loop:
	s_add_i32 s2, s0, s1
	s_cmp_lt_u32 s2, 0x8000
	s_cbranch_scc0 .Lpn_last_a
	s_lshl_b32 s17, s2, 12
	s_add_u32 s10, s6, s17
	s_addc_u32 s11, s7, 0
	global_load_dwordx4 v[56:59], v2, s[10:11]
	global_load_dwordx4 v[60:63], v2, s[10:11] offset:1024
	global_load_dwordx4 v[64:67], v2, s[10:11] offset:2048
	global_load_dwordx4 v[68:71], v2, s[10:11] offset:3072
	s_add_u32 s14, s90, s17
	s_addc_u32 s15, s91, 0
	global_load_dwordx4 v[72:75], v2, s[14:15]
	global_load_dwordx4 v[76:79], v2, s[14:15] offset:1024
	global_load_dwordx4 v[80:83], v2, s[14:15] offset:2048
	global_load_dwordx4 v[84:87], v2, s[14:15] offset:3072
	s_lshr_b32 s18, s2, 13
	s_mul_i32 s18, s18, 0x6000
	s_add_u32 s10, s8, s18
	s_addc_u32 s11, s9, 0
	global_load_dwordx4 v[88:91], v2, s[10:11]
	global_load_dwordx4 v[92:95], v2, s[10:11] offset:1024
	global_load_dwordx4 v[96:99], v2, s[10:11] offset:2048
	global_load_dwordx4 v[100:103], v2, s[10:11] offset:3072
	s_cmp_eq_u32 s16, 1
	s_cbranch_scc1 .Lpn_first_a
	s_waitcnt vmcnt(16)
	s_branch .Lpn_go_a
.Lpn_first_a:
	s_waitcnt vmcnt(12)
	s_mov_b32 s16, 0
; DI float wave_sum(float v) { v = row16_sum(v); v += __shfl_xor(v, 16); v += __shfl_xor(v, 32); return v; }
; __device__ void phase_peer_n(const Params& p, int bid, int nb) {
;     ...
;       for (int q = 0; q < 4; ++q) {
;         const int d0 = 256 * q + 4 * lane;
;         float4 xa = *(const float4*)(xrow + d0), ga = *(const float4*)(gate + d0), ya = *(const float4*)(orow + d0);
;         zz[u][4 * q + 0] = ALPHA * xa.x + ga.x * ya.x; zz[u][4 * q + 1] = ALPHA * xa.y + ga.y * ya.y;
;         zz[u][4 * q + 2] = ALPHA * xa.z + ga.z * ya.z; zz[u][4 * q + 3] = ALPHA * xa.w + ga.w * ya.w;
;       }
;     }
; #pragma unroll
;     for (int u = 0; u < NR; ++u) {
;       float s = 0.f;
; #pragma unroll
;       for (int k = 0; k < 16; ++k) s += zz[u][k];
;       mu[u] = wave_sum(s) * (1.f / 1024.f);
;     }
; #pragma unroll
;     for (int u = 0; u < NR; ++u) {
;       float q2 = 0.f;
; #pragma unroll
;       for (int k = 0; k < 16; ++k) { float d = zz[u][k] - mu[u]; q2 += d * d; }
;       rstd[u] = rsqrtf(wave_sum(q2) * (1.f / 1024.f) + LN_EPS);
;     }
; #pragma unroll
;     for (int u = 0; u < NR; ++u) {
;       if (u > 0 && tb + u * stride >= NTOK) break;
;       float* orow = p.out + (size_t)tt[u] * 1024;
; #pragma unroll
;       for (int q = 0; q < 4; ++q) {
;         const int d0 = 256 * q + 4 * lane;
;         float4 g4 = *(const float4*)(p.ln2_g + d0), b4 = *(const float4*)(p.ln2_b + d0);
;         *(float4*)(orow + d0) = make_float4((zz[u][4 * q + 0] - mu[u]) * rstd[u] * g4.x + b4.x, (zz[u][4 * q + 1] - mu[u]) * rstd[u] * g4.y + b4.y,
;                                             (zz[u][4 * q + 2] - mu[u]) * rstd[u] * g4.z + b4.z, (zz[u][4 * q + 3] - mu[u]) * rstd[u] * g4.w + b4.w);
;       }
.Lpn_go_a:
	v_mul_f32_e32 v40, v40, v24
	v_mul_f32_e32 v41, v41, v25
	v_mul_f32_e32 v42, v42, v26
	v_mul_f32_e32 v43, v43, v27
	v_mul_f32_e32 v44, v44, v28
	v_mul_f32_e32 v45, v45, v29
	v_mul_f32_e32 v46, v46, v30
	v_mul_f32_e32 v47, v47, v31
	v_mul_f32_e32 v48, v48, v32
	v_mul_f32_e32 v49, v49, v33
	v_mul_f32_e32 v50, v50, v34
	v_mul_f32_e32 v51, v51, v35
	v_mul_f32_e32 v52, v52, v36
	v_mul_f32_e32 v53, v53, v37
	v_mul_f32_e32 v54, v54, v38
	v_mul_f32_e32 v55, v55, v39
	v_fmac_f32_e32 v40, 0x3f9837f0, v8
	v_fmac_f32_e32 v41, 0x3f9837f0, v9
	v_fmac_f32_e32 v42, 0x3f9837f0, v10
	v_fmac_f32_e32 v43, 0x3f9837f0, v11
	v_fmac_f32_e32 v44, 0x3f9837f0, v12
	v_fmac_f32_e32 v45, 0x3f9837f0, v13
	v_fmac_f32_e32 v46, 0x3f9837f0, v14
	v_fmac_f32_e32 v47, 0x3f9837f0, v15
	v_fmac_f32_e32 v48, 0x3f9837f0, v16
	v_fmac_f32_e32 v49, 0x3f9837f0, v17
	v_fmac_f32_e32 v50, 0x3f9837f0, v18
	v_fmac_f32_e32 v51, 0x3f9837f0, v19
	v_fmac_f32_e32 v52, 0x3f9837f0, v20
	v_fmac_f32_e32 v53, 0x3f9837f0, v21
	v_fmac_f32_e32 v54, 0x3f9837f0, v22
	v_fmac_f32_e32 v55, 0x3f9837f0, v23
	v_add_f32_e32 v104, v40, v41
	v_add_f32_e32 v104, v104, v42
	v_add_f32_e32 v104, v104, v43
	v_add_f32_e32 v104, v104, v44
	v_add_f32_e32 v104, v104, v45
	v_add_f32_e32 v104, v104, v46
	v_add_f32_e32 v104, v104, v47
	v_add_f32_e32 v104, v104, v48
	v_add_f32_e32 v104, v104, v49
	v_add_f32_e32 v104, v104, v50
	v_add_f32_e32 v104, v104, v51
	v_add_f32_e32 v104, v104, v52
	v_add_f32_e32 v104, v104, v53
	v_add_f32_e32 v104, v104, v54
	v_add_f32_e32 v104, v104, v55
	s_nop 1
	v_add_f32_dpp v104, v104, v104 quad_perm:[1,0,3,2] row_mask:0xf bank_mask:0xf bound_ctrl:1
	s_nop 1
	v_add_f32_dpp v104, v104, v104 quad_perm:[2,3,0,1] row_mask:0xf bank_mask:0xf bound_ctrl:1
	s_nop 1
	v_add_f32_dpp v104, v104, v104 row_ror:4 row_mask:0xf bank_mask:0xf bound_ctrl:1
	s_nop 1
	v_add_f32_dpp v104, v104, v104 row_ror:8 row_mask:0xf bank_mask:0xf bound_ctrl:1
	v_mov_b32_e32 v105, v104
	s_nop 1
	v_permlane16_swap_b32_e32 v104, v105
	v_add_f32_e32 v104, v104, v105
	v_mov_b32_e32 v105, v104
	s_nop 1
	v_permlane32_swap_b32_e32 v104, v105
	v_add_f32_e32 v104, v104, v105
	v_mul_f32_e32 v107, 0x3a800000, v104
	v_sub_f32_e32 v40, v40, v107
	v_sub_f32_e32 v41, v41, v107
	v_sub_f32_e32 v42, v42, v107
	v_sub_f32_e32 v43, v43, v107
	v_sub_f32_e32 v44, v44, v107
	v_sub_f32_e32 v45, v45, v107
	v_sub_f32_e32 v46, v46, v107
	v_sub_f32_e32 v47, v47, v107
	v_sub_f32_e32 v48, v48, v107
	v_sub_f32_e32 v49, v49, v107
	v_sub_f32_e32 v50, v50, v107
	v_sub_f32_e32 v51, v51, v107
	v_sub_f32_e32 v52, v52, v107
	v_sub_f32_e32 v53, v53, v107
	v_sub_f32_e32 v54, v54, v107
	v_sub_f32_e32 v55, v55, v107
	v_mul_f32_e32 v104, v40, v40
	v_fmac_f32_e32 v104, v41, v41
	v_fmac_f32_e32 v104, v42, v42
	v_fmac_f32_e32 v104, v43, v43
	v_fmac_f32_e32 v104, v44, v44
	v_fmac_f32_e32 v104, v45, v45
	v_fmac_f32_e32 v104, v46, v46
	v_fmac_f32_e32 v104, v47, v47
	v_fmac_f32_e32 v104, v48, v48
	v_fmac_f32_e32 v104, v49, v49
	v_fmac_f32_e32 v104, v50, v50
	v_fmac_f32_e32 v104, v51, v51
	v_fmac_f32_e32 v104, v52, v52
	v_fmac_f32_e32 v104, v53, v53
	v_fmac_f32_e32 v104, v54, v54
	v_fmac_f32_e32 v104, v55, v55
	s_nop 1
	v_add_f32_dpp v104, v104, v104 quad_perm:[1,0,3,2] row_mask:0xf bank_mask:0xf bound_ctrl:1
	s_nop 1
	v_add_f32_dpp v104, v104, v104 quad_perm:[2,3,0,1] row_mask:0xf bank_mask:0xf bound_ctrl:1
	s_nop 1
	v_add_f32_dpp v104, v104, v104 row_ror:4 row_mask:0xf bank_mask:0xf bound_ctrl:1
	s_nop 1
	v_add_f32_dpp v104, v104, v104 row_ror:8 row_mask:0xf bank_mask:0xf bound_ctrl:1
	v_mov_b32_e32 v105, v104
	s_nop 1
	v_permlane16_swap_b32_e32 v104, v105
	v_add_f32_e32 v104, v104, v105
	v_mov_b32_e32 v105, v104
	s_nop 1
	v_permlane32_swap_b32_e32 v104, v105
	v_add_f32_e32 v104, v104, v105
	v_fmamk_f32 v104, v104, 0x3a800000, v3
	v_rsq_f32_e32 v106, v104
	s_nop 0
	v_mul_f32_e32 v40, v40, v106
	v_mul_f32_e32 v41, v41, v106
	v_mul_f32_e32 v42, v42, v106
	v_mul_f32_e32 v43, v43, v106
	v_mul_f32_e32 v44, v44, v106
	v_mul_f32_e32 v45, v45, v106
	v_mul_f32_e32 v46, v46, v106
	v_mul_f32_e32 v47, v47, v106
	v_mul_f32_e32 v48, v48, v106
	v_mul_f32_e32 v49, v49, v106
	v_mul_f32_e32 v50, v50, v106
	v_mul_f32_e32 v51, v51, v106
	v_mul_f32_e32 v52, v52, v106
	v_mul_f32_e32 v53, v53, v106
	v_mul_f32_e32 v54, v54, v106
	v_mul_f32_e32 v55, v55, v106
	v_fma_f32 v40, v40, v200, v216
	v_fma_f32 v41, v41, v201, v217
	v_fma_f32 v42, v42, v202, v218
	v_fma_f32 v43, v43, v203, v219
	v_fma_f32 v44, v44, v204, v220
	v_fma_f32 v45, v45, v205, v221
	v_fma_f32 v46, v46, v206, v222
	v_fma_f32 v47, v47, v207, v223
	v_fma_f32 v48, v48, v208, v224
	v_fma_f32 v49, v49, v209, v225
	v_fma_f32 v50, v50, v210, v226
	v_fma_f32 v51, v51, v211, v227
	v_fma_f32 v52, v52, v212, v228
	v_fma_f32 v53, v53, v213, v229
	v_fma_f32 v54, v54, v214, v230
	v_fma_f32 v55, v55, v215, v231
	global_store_dwordx4 v2, v[40:43], s[12:13]
	global_store_dwordx4 v2, v[44:47], s[12:13] offset:1024
	global_store_dwordx4 v2, v[48:51], s[12:13] offset:2048
	global_store_dwordx4 v2, v[52:55], s[12:13] offset:3072
	s_mov_b32 s0, s2
	s_add_i32 s2, s0, s1
	s_cmp_lt_u32 s2, 0x8000
	s_cbranch_scc0 .Lpn_last_b
	s_lshl_b32 s17, s2, 12
	s_add_u32 s10, s6, s17
	s_addc_u32 s11, s7, 0
	global_load_dwordx4 v[8:11], v2, s[10:11]
	global_load_dwordx4 v[12:15], v2, s[10:11] offset:1024
	global_load_dwordx4 v[16:19], v2, s[10:11] offset:2048
	global_load_dwordx4 v[20:23], v2, s[10:11] offset:3072
	s_add_u32 s12, s90, s17
	s_addc_u32 s13, s91, 0
	global_load_dwordx4 v[24:27], v2, s[12:13]
	global_load_dwordx4 v[28:31], v2, s[12:13] offset:1024
	global_load_dwordx4 v[32:35], v2, s[12:13] offset:2048
	global_load_dwordx4 v[36:39], v2, s[12:13] offset:3072
	s_lshr_b32 s18, s2, 13
	s_mul_i32 s18, s18, 0x6000
	s_add_u32 s10, s8, s18
	s_addc_u32 s11, s9, 0
	global_load_dwordx4 v[40:43], v2, s[10:11]
	global_load_dwordx4 v[44:47], v2, s[10:11] offset:1024
	global_load_dwordx4 v[48:51], v2, s[10:11] offset:2048
	global_load_dwordx4 v[52:55], v2, s[10:11] offset:3072
	s_cmp_eq_u32 s16, 1
	s_cbranch_scc1 .Lpn_first_b
	s_waitcnt vmcnt(16)
	s_branch .Lpn_go_b

; DI float wave_sum(float v) { v = row16_sum(v); v += __shfl_xor(v, 16); v += __shfl_xor(v, 32); return v; }
; __device__ void phase_peer_n(const Params& p, int bid, int nb) {
;     ...
;       for (int q = 0; q < 4; ++q) {
;         const int d0 = 256 * q + 4 * lane;
;         float4 xa = *(const float4*)(xrow + d0), ga = *(const float4*)(gate + d0), ya = *(const float4*)(orow + d0);
;         zz[u][4 * q + 0] = ALPHA * xa.x + ga.x * ya.x; zz[u][4 * q + 1] = ALPHA * xa.y + ga.y * ya.y;
;         zz[u][4 * q + 2] = ALPHA * xa.z + ga.z * ya.z; zz[u][4 * q + 3] = ALPHA * xa.w + ga.w * ya.w;
;       }
;     }
; #pragma unroll
;     for (int u = 0; u < NR; ++u) {
;       float s = 0.f;
; #pragma unroll
;       for (int k = 0; k < 16; ++k) s += zz[u][k];
;       mu[u] = wave_sum(s) * (1.f / 1024.f);
;     }
; #pragma unroll
;     for (int u = 0; u < NR; ++u) {
;       float q2 = 0.f;
; #pragma unroll
;       for (int k = 0; k < 16; ++k) { float d = zz[u][k] - mu[u]; q2 += d * d; }
;       rstd[u] = rsqrtf(wave_sum(q2) * (1.f / 1024.f) + LN_EPS);
;     }
; #pragma unroll
;     for (int u = 0; u < NR; ++u) {
;       if (u > 0 && tb + u * stride >= NTOK) break;
;       float* orow = p.out + (size_t)tt[u] * 1024;
; #pragma unroll
;       for (int q = 0; q < 4; ++q) {
;         const int d0 = 256 * q + 4 * lane;
;         float4 g4 = *(const float4*)(p.ln2_g + d0), b4 = *(const float4*)(p.ln2_b + d0);
;         *(float4*)(orow + d0) = make_float4((zz[u][4 * q + 0] - mu[u]) * rstd[u] * g4.x + b4.x, (zz[u][4 * q + 1] - mu[u]) * rstd[u] * g4.y + b4.y,
;                                             (zz[u][4 * q + 2] - mu[u]) * rstd[u] * g4.z + b4.z, (zz[u][4 * q + 3] - mu[u]) * rstd[u] * g4.w + b4.w);
;       }
.Lpn_go_b:
	v_mul_f32_e32 v88, v88, v72
	v_mul_f32_e32 v89, v89, v73
	v_mul_f32_e32 v90, v90, v74
	v_mul_f32_e32 v91, v91, v75
	v_mul_f32_e32 v92, v92, v76
	v_mul_f32_e32 v93, v93, v77
	v_mul_f32_e32 v94, v94, v78
	v_mul_f32_e32 v95, v95, v79
	v_mul_f32_e32 v96, v96, v80
	v_mul_f32_e32 v97, v97, v81
	v_mul_f32_e32 v98, v98, v82
	v_mul_f32_e32 v99, v99, v83
	v_mul_f32_e32 v100, v100, v84
	v_mul_f32_e32 v101, v101, v85
	v_mul_f32_e32 v102, v102, v86
	v_mul_f32_e32 v103, v103, v87
	v_fmac_f32_e32 v88, 0x3f9837f0, v56
	v_fmac_f32_e32 v89, 0x3f9837f0, v57
	v_fmac_f32_e32 v90, 0x3f9837f0, v58
	v_fmac_f32_e32 v91, 0x3f9837f0, v59
	v_fmac_f32_e32 v92, 0x3f9837f0, v60
	v_fmac_f32_e32 v93, 0x3f9837f0, v61
	v_fmac_f32_e32 v94, 0x3f9837f0, v62
	v_fmac_f32_e32 v95, 0x3f9837f0, v63
	v_fmac_f32_e32 v96, 0x3f9837f0, v64
	v_fmac_f32_e32 v97, 0x3f9837f0, v65
	v_fmac_f32_e32 v98, 0x3f9837f0, v66
	v_fmac_f32_e32 v99, 0x3f9837f0, v67
	v_fmac_f32_e32 v100, 0x3f9837f0, v68
	v_fmac_f32_e32 v101, 0x3f9837f0, v69
	v_fmac_f32_e32 v102, 0x3f9837f0, v70
	v_fmac_f32_e32 v103, 0x3f9837f0, v71
	v_add_f32_e32 v104, v88, v89
	v_add_f32_e32 v104, v104, v90
	v_add_f32_e32 v104, v104, v91
	v_add_f32_e32 v104, v104, v92
	v_add_f32_e32 v104, v104, v93
	v_add_f32_e32 v104, v104, v94
	v_add_f32_e32 v104, v104, v95
	v_add_f32_e32 v104, v104, v96
	v_add_f32_e32 v104, v104, v97
	v_add_f32_e32 v104, v104, v98
	v_add_f32_e32 v104, v104, v99
	v_add_f32_e32 v104, v104, v100
	v_add_f32_e32 v104, v104, v101
	v_add_f32_e32 v104, v104, v102
	v_add_f32_e32 v104, v104, v103
	s_nop 1
	v_add_f32_dpp v104, v104, v104 quad_perm:[1,0,3,2] row_mask:0xf bank_mask:0xf bound_ctrl:1
	s_nop 1
	v_add_f32_dpp v104, v104, v104 quad_perm:[2,3,0,1] row_mask:0xf bank_mask:0xf bound_ctrl:1
	s_nop 1
	v_add_f32_dpp v104, v104, v104 row_ror:4 row_mask:0xf bank_mask:0xf bound_ctrl:1
	s_nop 1
	v_add_f32_dpp v104, v104, v104 row_ror:8 row_mask:0xf bank_mask:0xf bound_ctrl:1
	v_mov_b32_e32 v105, v104
	s_nop 1
	v_permlane16_swap_b32_e32 v104, v105
	v_add_f32_e32 v104, v104, v105
	v_mov_b32_e32 v105, v104
	s_nop 1
	v_permlane32_swap_b32_e32 v104, v105
	v_add_f32_e32 v104, v104, v105
	v_mul_f32_e32 v107, 0x3a800000, v104
	v_sub_f32_e32 v88, v88, v107
	v_sub_f32_e32 v89, v89, v107
	v_sub_f32_e32 v90, v90, v107
	v_sub_f32_e32 v91, v91, v107
	v_sub_f32_e32 v92, v92, v107
	v_sub_f32_e32 v93, v93, v107
	v_sub_f32_e32 v94, v94, v107
	v_sub_f32_e32 v95, v95, v107
	v_sub_f32_e32 v96, v96, v107
	v_sub_f32_e32 v97, v97, v107
	v_sub_f32_e32 v98, v98, v107
	v_sub_f32_e32 v99, v99, v107
	v_sub_f32_e32 v100, v100, v107
	v_sub_f32_e32 v101, v101, v107
	v_sub_f32_e32 v102, v102, v107
	v_sub_f32_e32 v103, v103, v107
	v_mul_f32_e32 v104, v88, v88
	v_fmac_f32_e32 v104, v89, v89
	v_fmac_f32_e32 v104, v90, v90
	v_fmac_f32_e32 v104, v91, v91
	v_fmac_f32_e32 v104, v92, v92
	v_fmac_f32_e32 v104, v93, v93
	v_fmac_f32_e32 v104, v94, v94
	v_fmac_f32_e32 v104, v95, v95
	v_fmac_f32_e32 v104, v96, v96
	v_fmac_f32_e32 v104, v97, v97
	v_fmac_f32_e32 v104, v98, v98
	v_fmac_f32_e32 v104, v99, v99
	v_fmac_f32_e32 v104, v100, v100
	v_fmac_f32_e32 v104, v101, v101
	v_fmac_f32_e32 v104, v102, v102
	v_fmac_f32_e32 v104, v103, v103
	s_nop 1
	v_add_f32_dpp v104, v104, v104 quad_perm:[1,0,3,2] row_mask:0xf bank_mask:0xf bound_ctrl:1
	s_nop 1
	v_add_f32_dpp v104, v104, v104 quad_perm:[2,3,0,1] row_mask:0xf bank_mask:0xf bound_ctrl:1
	s_nop 1
	v_add_f32_dpp v104, v104, v104 row_ror:4 row_mask:0xf bank_mask:0xf bound_ctrl:1
	s_nop 1
	v_add_f32_dpp v104, v104, v104 row_ror:8 row_mask:0xf bank_mask:0xf bound_ctrl:1
	v_mov_b32_e32 v105, v104
	s_nop 1
	v_permlane16_swap_b32_e32 v104, v105
	v_add_f32_e32 v104, v104, v105
	v_mov_b32_e32 v105, v104
	s_nop 1
	v_permlane32_swap_b32_e32 v104, v105
	v_add_f32_e32 v104, v104, v105
	v_fmamk_f32 v104, v104, 0x3a800000, v3
	v_rsq_f32_e32 v106, v104
	s_nop 0
	v_mul_f32_e32 v88, v88, v106
	v_mul_f32_e32 v89, v89, v106
	v_mul_f32_e32 v90, v90, v106
	v_mul_f32_e32 v91, v91, v106
	v_mul_f32_e32 v92, v92, v106
	v_mul_f32_e32 v93, v93, v106
	v_mul_f32_e32 v94, v94, v106
	v_mul_f32_e32 v95, v95, v106
	v_mul_f32_e32 v96, v96, v106
	v_mul_f32_e32 v97, v97, v106
	v_mul_f32_e32 v98, v98, v106
	v_mul_f32_e32 v99, v99, v106
	v_mul_f32_e32 v100, v100, v106
	v_mul_f32_e32 v101, v101, v106
	v_mul_f32_e32 v102, v102, v106
	v_mul_f32_e32 v103, v103, v106
	v_fma_f32 v88, v88, v200, v216
	v_fma_f32 v89, v89, v201, v217
	v_fma_f32 v90, v90, v202, v218
	v_fma_f32 v91, v91, v203, v219
	v_fma_f32 v92, v92, v204, v220
	v_fma_f32 v93, v93, v205, v221
	v_fma_f32 v94, v94, v206, v222
	v_fma_f32 v95, v95, v207, v223
	v_fma_f32 v96, v96, v208, v224
	v_fma_f32 v97, v97, v209, v225
	v_fma_f32 v98, v98, v210, v226
	v_fma_f32 v99, v99, v211, v227
	v_fma_f32 v100, v100, v212, v228
	v_fma_f32 v101, v101, v213, v229
	v_fma_f32 v102, v102, v214, v230
	v_fma_f32 v103, v103, v215, v231
	global_store_dwordx4 v2, v[88:91], s[14:15]
	global_store_dwordx4 v2, v[92:95], s[14:15] offset:1024
	global_store_dwordx4 v2, v[96:99], s[14:15] offset:2048
	global_store_dwordx4 v2, v[100:103], s[14:15] offset:3072
	s_mov_b32 s0, s2
	s_branch .Lpn_loop
; DI float wave_sum(float v) { v = row16_sum(v); v += __shfl_xor(v, 16); v += __shfl_xor(v, 32); return v; }
; __device__ void phase_peer_n(const Params& p, int bid, int nb) {
;     ...
;       for (int q = 0; q < 4; ++q) {
;         const int d0 = 256 * q + 4 * lane;
;         float4 xa = *(const float4*)(xrow + d0), ga = *(const float4*)(gate + d0), ya = *(const float4*)(orow + d0);
;         zz[u][4 * q + 0] = ALPHA * xa.x + ga.x * ya.x; zz[u][4 * q + 1] = ALPHA * xa.y + ga.y * ya.y;
;         zz[u][4 * q + 2] = ALPHA * xa.z + ga.z * ya.z; zz[u][4 * q + 3] = ALPHA * xa.w + ga.w * ya.w;
;       }
;     }
; #pragma unroll
;     for (int u = 0; u < NR; ++u) {
;       float s = 0.f;
; #pragma unroll
;       for (int k = 0; k < 16; ++k) s += zz[u][k];
;       mu[u] = wave_sum(s) * (1.f / 1024.f);
;     }
; #pragma unroll
;     for (int u = 0; u < NR; ++u) {
;       float q2 = 0.f;
; #pragma unroll
;       for (int k = 0; k < 16; ++k) { float d = zz[u][k] - mu[u]; q2 += d * d; }
;       rstd[u] = rsqrtf(wave_sum(q2) * (1.f / 1024.f) + LN_EPS);
;     }
; #pragma unroll
;     for (int u = 0; u < NR; ++u) {
;       if (u > 0 && tb + u * stride >= NTOK) break;
;       float* orow = p.out + (size_t)tt[u] * 1024;
; #pragma unroll
;       for (int q = 0; q < 4; ++q) {
;         const int d0 = 256 * q + 4 * lane;
;         float4 g4 = *(const float4*)(p.ln2_g + d0), b4 = *(const float4*)(p.ln2_b + d0);
;         *(float4*)(orow + d0) = make_float4((zz[u][4 * q + 0] - mu[u]) * rstd[u] * g4.x + b4.x, (zz[u][4 * q + 1] - mu[u]) * rstd[u] * g4.y + b4.y,
;                                             (zz[u][4 * q + 2] - mu[u]) * rstd[u] * g4.z + b4.z, (zz[u][4 * q + 3] - mu[u]) * rstd[u] * g4.w + b4.w);
;       }
.Lpn_last_a:
	s_waitcnt vmcnt(0)
	v_mul_f32_e32 v40, v40, v24
	v_mul_f32_e32 v41, v41, v25
	v_mul_f32_e32 v42, v42, v26
	v_mul_f32_e32 v43, v43, v27
	v_mul_f32_e32 v44, v44, v28
	v_mul_f32_e32 v45, v45, v29
	v_mul_f32_e32 v46, v46, v30
	v_mul_f32_e32 v47, v47, v31
	v_mul_f32_e32 v48, v48, v32
	v_mul_f32_e32 v49, v49, v33
	v_mul_f32_e32 v50, v50, v34
	v_mul_f32_e32 v51, v51, v35
	v_mul_f32_e32 v52, v52, v36
	v_mul_f32_e32 v53, v53, v37
	v_mul_f32_e32 v54, v54, v38
	v_mul_f32_e32 v55, v55, v39
	v_fmac_f32_e32 v40, 0x3f9837f0, v8
	v_fmac_f32_e32 v41, 0x3f9837f0, v9
	v_fmac_f32_e32 v42, 0x3f9837f0, v10
	v_fmac_f32_e32 v43, 0x3f9837f0, v11
	v_fmac_f32_e32 v44, 0x3f9837f0, v12
	v_fmac_f32_e32 v45, 0x3f9837f0, v13
	v_fmac_f32_e32 v46, 0x3f9837f0, v14
	v_fmac_f32_e32 v47, 0x3f9837f0, v15
	v_fmac_f32_e32 v48, 0x3f9837f0, v16
	v_fmac_f32_e32 v49, 0x3f9837f0, v17
	v_fmac_f32_e32 v50, 0x3f9837f0, v18
	v_fmac_f32_e32 v51, 0x3f9837f0, v19
	v_fmac_f32_e32 v52, 0x3f9837f0, v20
	v_fmac_f32_e32 v53, 0x3f9837f0, v21
	v_fmac_f32_e32 v54, 0x3f9837f0, v22
	v_fmac_f32_e32 v55, 0x3f9837f0, v23
	v_add_f32_e32 v104, v40, v41
	v_add_f32_e32 v104, v104, v42
	v_add_f32_e32 v104, v104, v43
	v_add_f32_e32 v104, v104, v44
	v_add_f32_e32 v104, v104, v45
	v_add_f32_e32 v104, v104, v46
	v_add_f32_e32 v104, v104, v47
	v_add_f32_e32 v104, v104, v48
	v_add_f32_e32 v104, v104, v49
	v_add_f32_e32 v104, v104, v50
	v_add_f32_e32 v104, v104, v51
	v_add_f32_e32 v104, v104, v52
	v_add_f32_e32 v104, v104, v53
	v_add_f32_e32 v104, v104, v54
	v_add_f32_e32 v104, v104, v55
	s_nop 1
	v_add_f32_dpp v104, v104, v104 quad_perm:[1,0,3,2] row_mask:0xf bank_mask:0xf bound_ctrl:1
	s_nop 1
	v_add_f32_dpp v104, v104, v104 quad_perm:[2,3,0,1] row_mask:0xf bank_mask:0xf bound_ctrl:1
	s_nop 1
	v_add_f32_dpp v104, v104, v104 row_ror:4 row_mask:0xf bank_mask:0xf bound_ctrl:1
	s_nop 1
	v_add_f32_dpp v104, v104, v104 row_ror:8 row_mask:0xf bank_mask:0xf bound_ctrl:1
	v_mov_b32_e32 v105, v104
	s_nop 1
	v_permlane16_swap_b32_e32 v104, v105
	v_add_f32_e32 v104, v104, v105
	v_mov_b32_e32 v105, v104
	s_nop 1
	v_permlane32_swap_b32_e32 v104, v105
	v_add_f32_e32 v104, v104, v105
	v_mul_f32_e32 v107, 0x3a800000, v104
	v_sub_f32_e32 v40, v40, v107
	v_sub_f32_e32 v41, v41, v107
	v_sub_f32_e32 v42, v42, v107
	v_sub_f32_e32 v43, v43, v107
	v_sub_f32_e32 v44, v44, v107
	v_sub_f32_e32 v45, v45, v107
	v_sub_f32_e32 v46, v46, v107
	v_sub_f32_e32 v47, v47, v107
	v_sub_f32_e32 v48, v48, v107
	v_sub_f32_e32 v49, v49, v107
	v_sub_f32_e32 v50, v50, v107
	v_sub_f32_e32 v51, v51, v107
	v_sub_f32_e32 v52, v52, v107
	v_sub_f32_e32 v53, v53, v107
	v_sub_f32_e32 v54, v54, v107
	v_sub_f32_e32 v55, v55, v107
	v_mul_f32_e32 v104, v40, v40
	v_fmac_f32_e32 v104, v41, v41
	v_fmac_f32_e32 v104, v42, v42
	v_fmac_f32_e32 v104, v43, v43
	v_fmac_f32_e32 v104, v44, v44
	v_fmac_f32_e32 v104, v45, v45
	v_fmac_f32_e32 v104, v46, v46
	v_fmac_f32_e32 v104, v47, v47
	v_fmac_f32_e32 v104, v48, v48
	v_fmac_f32_e32 v104, v49, v49
	v_fmac_f32_e32 v104, v50, v50
	v_fmac_f32_e32 v104, v51, v51
	v_fmac_f32_e32 v104, v52, v52
	v_fmac_f32_e32 v104, v53, v53
	v_fmac_f32_e32 v104, v54, v54
	v_fmac_f32_e32 v104, v55, v55
	s_nop 1
	v_add_f32_dpp v104, v104, v104 quad_perm:[1,0,3,2] row_mask:0xf bank_mask:0xf bound_ctrl:1
	s_nop 1
	v_add_f32_dpp v104, v104, v104 quad_perm:[2,3,0,1] row_mask:0xf bank_mask:0xf bound_ctrl:1
	s_nop 1
	v_add_f32_dpp v104, v104, v104 row_ror:4 row_mask:0xf bank_mask:0xf bound_ctrl:1
	s_nop 1
	v_add_f32_dpp v104, v104, v104 row_ror:8 row_mask:0xf bank_mask:0xf bound_ctrl:1
	v_mov_b32_e32 v105, v104
	s_nop 1
	v_permlane16_swap_b32_e32 v104, v105
	v_add_f32_e32 v104, v104, v105
	v_mov_b32_e32 v105, v104
	s_nop 1
	v_permlane32_swap_b32_e32 v104, v105
	v_add_f32_e32 v104, v104, v105
	v_fmamk_f32 v104, v104, 0x3a800000, v3
	v_rsq_f32_e32 v106, v104
	s_nop 0
	v_mul_f32_e32 v40, v40, v106
	v_mul_f32_e32 v41, v41, v106
	v_mul_f32_e32 v42, v42, v106
	v_mul_f32_e32 v43, v43, v106
	v_mul_f32_e32 v44, v44, v106
	v_mul_f32_e32 v45, v45, v106
	v_mul_f32_e32 v46, v46, v106
	v_mul_f32_e32 v47, v47, v106
	v_mul_f32_e32 v48, v48, v106
	v_mul_f32_e32 v49, v49, v106
	v_mul_f32_e32 v50, v50, v106
	v_mul_f32_e32 v51, v51, v106
	v_mul_f32_e32 v52, v52, v106
	v_mul_f32_e32 v53, v53, v106
	v_mul_f32_e32 v54, v54, v106
	v_mul_f32_e32 v55, v55, v106
	v_fma_f32 v40, v40, v200, v216
	v_fma_f32 v41, v41, v201, v217
	v_fma_f32 v42, v42, v202, v218
	v_fma_f32 v43, v43, v203, v219
	v_fma_f32 v44, v44, v204, v220
	v_fma_f32 v45, v45, v205, v221
	v_fma_f32 v46, v46, v206, v222
	v_fma_f32 v47, v47, v207, v223
	v_fma_f32 v48, v48, v208, v224
	v_fma_f32 v49, v49, v209, v225
	v_fma_f32 v50, v50, v210, v226
	v_fma_f32 v51, v51, v211, v227
	v_fma_f32 v52, v52, v212, v228
	v_fma_f32 v53, v53, v213, v229
	v_fma_f32 v54, v54, v214, v230
	v_fma_f32 v55, v55, v215, v231
	global_store_dwordx4 v2, v[40:43], s[12:13]
	global_store_dwordx4 v2, v[44:47], s[12:13] offset:1024
	global_store_dwordx4 v2, v[48:51], s[12:13] offset:2048
	global_store_dwordx4 v2, v[52:55], s[12:13] offset:3072
	s_branch .LBB0_785
; DI float wave_sum(float v) { v = row16_sum(v); v += __shfl_xor(v, 16); v += __shfl_xor(v, 32); return v; }
; __device__ void phase_peer_n(const Params& p, int bid, int nb) {
;     ...
;       for (int q = 0; q < 4; ++q) {
;         const int d0 = 256 * q + 4 * lane;
;         float4 xa = *(const float4*)(xrow + d0), ga = *(const float4*)(gate + d0), ya = *(const float4*)(orow + d0);
;         zz[u][4 * q + 0] = ALPHA * xa.x + ga.x * ya.x; zz[u][4 * q + 1] = ALPHA * xa.y + ga.y * ya.y;
;         zz[u][4 * q + 2] = ALPHA * xa.z + ga.z * ya.z; zz[u][4 * q + 3] = ALPHA * xa.w + ga.w * ya.w;
;       }
;     }
; #pragma unroll
;     for (int u = 0; u < NR; ++u) {
;       float s = 0.f;
; #pragma unroll
;       for (int k = 0; k < 16; ++k) s += zz[u][k];
;       mu[u] = wave_sum(s) * (1.f / 1024.f);
;     }
; #pragma unroll
;     for (int u = 0; u < NR; ++u) {
;       float q2 = 0.f;
; #pragma unroll
;       for (int k = 0; k < 16; ++k) { float d = zz[u][k] - mu[u]; q2 += d * d; }
;       rstd[u] = rsqrtf(wave_sum(q2) * (1.f / 1024.f) + LN_EPS);
;     }
; #pragma unroll
;     for (int u = 0; u < NR; ++u) {
;       if (u > 0 && tb + u * stride >= NTOK) break;
;       float* orow = p.out + (size_t)tt[u] * 1024;
; #pragma unroll
;       for (int q = 0; q < 4; ++q) {
;         const int d0 = 256 * q + 4 * lane;
;         float4 g4 = *(const float4*)(p.ln2_g + d0), b4 = *(const float4*)(p.ln2_b + d0);
;         *(float4*)(orow + d0) = make_float4((zz[u][4 * q + 0] - mu[u]) * rstd[u] * g4.x + b4.x, (zz[u][4 * q + 1] - mu[u]) * rstd[u] * g4.y + b4.y,
;                                             (zz[u][4 * q + 2] - mu[u]) * rstd[u] * g4.z + b4.z, (zz[u][4 * q + 3] - mu[u]) * rstd[u] * g4.w + b4.w);
;       }
.Lpn_last_b:
	s_waitcnt vmcnt(0)
	v_mul_f32_e32 v88, v88, v72
	v_mul_f32_e32 v89, v89, v73
	v_mul_f32_e32 v90, v90, v74
	v_mul_f32_e32 v91, v91, v75
	v_mul_f32_e32 v92, v92, v76
	v_mul_f32_e32 v93, v93, v77
	v_mul_f32_e32 v94, v94, v78
	v_mul_f32_e32 v95, v95, v79
	v_mul_f32_e32 v96, v96, v80
	v_mul_f32_e32 v97, v97, v81
	v_mul_f32_e32 v98, v98, v82
	v_mul_f32_e32 v99, v99, v83
	v_mul_f32_e32 v100, v100, v84
	v_mul_f32_e32 v101, v101, v85
	v_mul_f32_e32 v102, v102, v86
	v_mul_f32_e32 v103, v103, v87
	v_fmac_f32_e32 v88, 0x3f9837f0, v56
	v_fmac_f32_e32 v89, 0x3f9837f0, v57
	v_fmac_f32_e32 v90, 0x3f9837f0, v58
	v_fmac_f32_e32 v91, 0x3f9837f0, v59
	v_fmac_f32_e32 v92, 0x3f9837f0, v60
	v_fmac_f32_e32 v93, 0x3f9837f0, v61
	v_fmac_f32_e32 v94, 0x3f9837f0, v62
	v_fmac_f32_e32 v95, 0x3f9837f0, v63
	v_fmac_f32_e32 v96, 0x3f9837f0, v64
	v_fmac_f32_e32 v97, 0x3f9837f0, v65
	v_fmac_f32_e32 v98, 0x3f9837f0, v66
	v_fmac_f32_e32 v99, 0x3f9837f0, v67
	v_fmac_f32_e32 v100, 0x3f9837f0, v68
	v_fmac_f32_e32 v101, 0x3f9837f0, v69
	v_fmac_f32_e32 v102, 0x3f9837f0, v70
	v_fmac_f32_e32 v103, 0x3f9837f0, v71
	v_add_f32_e32 v104, v88, v89
	v_add_f32_e32 v104, v104, v90
	v_add_f32_e32 v104, v104, v91
	v_add_f32_e32 v104, v104, v92
	v_add_f32_e32 v104, v104, v93
	v_add_f32_e32 v104, v104, v94
	v_add_f32_e32 v104, v104, v95
	v_add_f32_e32 v104, v104, v96
	v_add_f32_e32 v104, v104, v97
	v_add_f32_e32 v104, v104, v98
	v_add_f32_e32 v104, v104, v99
	v_add_f32_e32 v104, v104, v100
	v_add_f32_e32 v104, v104, v101
	v_add_f32_e32 v104, v104, v102
	v_add_f32_e32 v104, v104, v103
	s_nop 1
	v_add_f32_dpp v104, v104, v104 quad_perm:[1,0,3,2] row_mask:0xf bank_mask:0xf bound_ctrl:1
	s_nop 1
	v_add_f32_dpp v104, v104, v104 quad_perm:[2,3,0,1] row_mask:0xf bank_mask:0xf bound_ctrl:1
	s_nop 1
	v_add_f32_dpp v104, v104, v104 row_ror:4 row_mask:0xf bank_mask:0xf bound_ctrl:1
	s_nop 1
	v_add_f32_dpp v104, v104, v104 row_ror:8 row_mask:0xf bank_mask:0xf bound_ctrl:1
	v_mov_b32_e32 v105, v104
	s_nop 1
	v_permlane16_swap_b32_e32 v104, v105
	v_add_f32_e32 v104, v104, v105
	v_mov_b32_e32 v105, v104
	s_nop 1
	v_permlane32_swap_b32_e32 v104, v105
	v_add_f32_e32 v104, v104, v105
	v_mul_f32_e32 v107, 0x3a800000, v104
	v_sub_f32_e32 v88, v88, v107
	v_sub_f32_e32 v89, v89, v107
	v_sub_f32_e32 v90, v90, v107
	v_sub_f32_e32 v91, v91, v107
	v_sub_f32_e32 v92, v92, v107
	v_sub_f32_e32 v93, v93, v107
	v_sub_f32_e32 v94, v94, v107
	v_sub_f32_e32 v95, v95, v107
	v_sub_f32_e32 v96, v96, v107
	v_sub_f32_e32 v97, v97, v107
	v_sub_f32_e32 v98, v98, v107
	v_sub_f32_e32 v99, v99, v107
	v_sub_f32_e32 v100, v100, v107
	v_sub_f32_e32 v101, v101, v107
	v_sub_f32_e32 v102, v102, v107
	v_sub_f32_e32 v103, v103, v107
	v_mul_f32_e32 v104, v88, v88
	v_fmac_f32_e32 v104, v89, v89
	v_fmac_f32_e32 v104, v90, v90
	v_fmac_f32_e32 v104, v91, v91
	v_fmac_f32_e32 v104, v92, v92
	v_fmac_f32_e32 v104, v93, v93
	v_fmac_f32_e32 v104, v94, v94
	v_fmac_f32_e32 v104, v95, v95
	v_fmac_f32_e32 v104, v96, v96
	v_fmac_f32_e32 v104, v97, v97
	v_fmac_f32_e32 v104, v98, v98
	v_fmac_f32_e32 v104, v99, v99
	v_fmac_f32_e32 v104, v100, v100
	v_fmac_f32_e32 v104, v101, v101
	v_fmac_f32_e32 v104, v102, v102
	v_fmac_f32_e32 v104, v103, v103
	s_nop 1
	v_add_f32_dpp v104, v104, v104 quad_perm:[1,0,3,2] row_mask:0xf bank_mask:0xf bound_ctrl:1
	s_nop 1
	v_add_f32_dpp v104, v104, v104 quad_perm:[2,3,0,1] row_mask:0xf bank_mask:0xf bound_ctrl:1
	s_nop 1
	v_add_f32_dpp v104, v104, v104 row_ror:4 row_mask:0xf bank_mask:0xf bound_ctrl:1
	s_nop 1
	v_add_f32_dpp v104, v104, v104 row_ror:8 row_mask:0xf bank_mask:0xf bound_ctrl:1
	v_mov_b32_e32 v105, v104
	s_nop 1
	v_permlane16_swap_b32_e32 v104, v105
	v_add_f32_e32 v104, v104, v105
	v_mov_b32_e32 v105, v104
	s_nop 1
	v_permlane32_swap_b32_e32 v104, v105
	v_add_f32_e32 v104, v104, v105
	v_fmamk_f32 v104, v104, 0x3a800000, v3
	v_rsq_f32_e32 v106, v104
	s_nop 0
	v_mul_f32_e32 v88, v88, v106
	v_mul_f32_e32 v89, v89, v106
	v_mul_f32_e32 v90, v90, v106
	v_mul_f32_e32 v91, v91, v106
	v_mul_f32_e32 v92, v92, v106
	v_mul_f32_e32 v93, v93, v106
	v_mul_f32_e32 v94, v94, v106
	v_mul_f32_e32 v95, v95, v106
	v_mul_f32_e32 v96, v96, v106
	v_mul_f32_e32 v97, v97, v106
	v_mul_f32_e32 v98, v98, v106
	v_mul_f32_e32 v99, v99, v106
	v_mul_f32_e32 v100, v100, v106
	v_mul_f32_e32 v101, v101, v106
	v_mul_f32_e32 v102, v102, v106
	v_mul_f32_e32 v103, v103, v106
	v_fma_f32 v88, v88, v200, v216
	v_fma_f32 v89, v89, v201, v217
	v_fma_f32 v90, v90, v202, v218
	v_fma_f32 v91, v91, v203, v219
	v_fma_f32 v92, v92, v204, v220
	v_fma_f32 v93, v93, v205, v221
	v_fma_f32 v94, v94, v206, v222
	v_fma_f32 v95, v95, v207, v223
	v_fma_f32 v96, v96, v208, v224
	v_fma_f32 v97, v97, v209, v225
	v_fma_f32 v98, v98, v210, v226
	v_fma_f32 v99, v99, v211, v227
	v_fma_f32 v100, v100, v212, v228
	v_fma_f32 v101, v101, v213, v229
	v_fma_f32 v102, v102, v214, v230
	v_fma_f32 v103, v103, v215, v231
	global_store_dwordx4 v2, v[88:91], s[14:15]
	global_store_dwordx4 v2, v[92:95], s[14:15] offset:1024
	global_store_dwordx4 v2, v[96:99], s[14:15] offset:2048
	global_store_dwordx4 v2, v[100:103], s[14:15] offset:3072
	s_branch .LBB0_785
